# P8 fused epilogue ladder with 6 X1B loads in flight (own offsets, spare quads), loads-only wait counts; on v97
# baseline (speedup 1.0000x reference)
.LBB0_1042:
	s_or_b64 exec, exec, s[4:5]
	v_add_u32_e32 v148, s3, v1
	v_ashrrev_i32_e32 v149, 31, v148
	s_waitcnt lgkmcnt(0)
	v_lshlrev_b64 v[150:151], 11, v[148:149]
	v_lshl_add_u64 v[154:155], v[150:151], 0, v[146:147]
	s_waitcnt lgkmcnt(0)
	s_barrier
	v_lshl_add_u64 v[156:157], v[154:155], 1, s[52:53]
	v_lshl_add_u32 v232, v148, 11, v146
	v_lshlrev_b32_e32 v232, 1, v232
	global_load_dwordx4 v[236:239], v232, s[52:53] nt
	global_load_dwordx4 v[240:243], v232, s[52:53] offset:256 nt
	v_add_u32_e32 v233, 0x10000, v232
	global_load_dwordx4 v[244:247], v233, s[52:53] nt
	v_add_u32_e32 v233, 0x10000, v232
	global_load_dwordx4 v[248:251], v233, s[52:53] offset:256 nt
	v_add_u32_e32 v233, 0x20000, v232
	global_load_dwordx4 v[228:231], v233, s[52:53] nt
	v_add_u32_e32 v233, 0x20000, v232
	global_load_dwordx4 v[222:225], v233, s[52:53] offset:256 nt
	v_lshl_add_u32 v1, v1, 2, 0
	ds_read_b32 v158, v1 offset:8192
	v_lshl_add_u64 v[154:155], v[154:155], 2, s[24:25]
	s_waitcnt lgkmcnt(0)
	v_pk_mul_f32 v[126:127], v[126:127], v[158:159] op_sel_hi:[1,0]
	v_pk_mul_f32 v[128:129], v[128:129], v[158:159] op_sel_hi:[1,0]
	v_pk_mul_f32 v[160:161], v[122:123], v[158:159] op_sel_hi:[1,0]
	v_pk_mul_f32 v[162:163], v[124:125], v[158:159] op_sel_hi:[1,0]
	v_pk_mul_f32 v[118:119], v[118:119], v[158:159] op_sel_hi:[1,0]
	v_pk_mul_f32 v[120:121], v[120:121], v[158:159] op_sel_hi:[1,0]
	s_waitcnt vmcnt(5)
	v_mov_b32_e32 v150, v236
	v_mov_b32_e32 v151, v237
	v_mov_b32_e32 v152, v238
	v_mov_b32_e32 v153, v239
	v_add_u32_e32 v233, 0x30000, v232
	global_load_dwordx4 v[236:239], v233, s[52:53] nt
	v_lshlrev_b32_e32 v122, 16, v150
	v_and_b32_e32 v123, 0xffff0000, v150
	v_lshlrev_b32_e32 v124, 16, v151
	v_and_b32_e32 v125, 0xffff0000, v151
	v_lshlrev_b32_e32 v150, 16, v152
	v_and_b32_e32 v151, 0xffff0000, v152
	v_lshlrev_b32_e32 v152, 16, v153
	v_and_b32_e32 v153, 0xffff0000, v153
	v_pk_fma_f32 v[124:125], v[144:145], v[128:129], v[124:125]
	v_pk_fma_f32 v[122:123], v[142:143], v[126:127], v[122:123]
	v_pk_fma_f32 v[128:129], v[140:141], v[162:163], v[152:153]
	v_pk_fma_f32 v[126:127], v[138:139], v[160:161], v[150:151]
	global_store_dwordx4 v[154:155], v[122:125], off nt
	global_store_dwordx4 v[154:155], v[126:129], off offset:16 nt
	s_nop 1
	v_pk_mul_f32 v[150:151], v[114:115], v[158:159] op_sel_hi:[1,0]
	v_add_u32_e32 v126, 16, v148
	v_ashrrev_i32_e32 v127, 31, v126
	v_pk_mul_f32 v[152:153], v[116:117], v[158:159] op_sel_hi:[1,0]
	v_lshlrev_b64 v[126:127], 11, v[126:127]
	v_lshl_add_u64 v[126:127], v[126:127], 0, v[146:147]
	v_lshl_add_u64 v[128:129], v[126:127], 1, s[52:53]
	s_waitcnt vmcnt(5)
	v_mov_b32_e32 v122, v240
	v_mov_b32_e32 v123, v241
	v_mov_b32_e32 v124, v242
	v_mov_b32_e32 v125, v243
	v_add_u32_e32 v233, 0x30000, v232
	global_load_dwordx4 v[240:243], v233, s[52:53] offset:256 nt
	v_lshlrev_b32_e32 v114, 16, v122
	v_and_b32_e32 v115, 0xffff0000, v122
	v_lshlrev_b32_e32 v116, 16, v123
	v_and_b32_e32 v117, 0xffff0000, v123
	v_lshlrev_b32_e32 v122, 16, v124
	v_and_b32_e32 v123, 0xffff0000, v124
	v_lshlrev_b32_e32 v124, 16, v125
	v_and_b32_e32 v125, 0xffff0000, v125
	v_pk_fma_f32 v[116:117], v[136:137], v[120:121], v[116:117]
	v_pk_fma_f32 v[114:115], v[134:135], v[118:119], v[114:115]
	v_pk_fma_f32 v[120:121], v[132:133], v[152:153], v[124:125]
	v_pk_fma_f32 v[118:119], v[130:131], v[150:151], v[122:123]
	global_store_dwordx4 v[154:155], v[114:117], off offset:512 nt
	global_store_dwordx4 v[154:155], v[118:121], off offset:528 nt
	s_nop 1
	ds_read_b32 v118, v1 offset:8256
	v_lshl_add_u64 v[120:121], v[126:127], 2, s[24:25]
	s_waitcnt lgkmcnt(0)
	v_pk_mul_f32 v[110:111], v[110:111], v[118:119] op_sel_hi:[1,0]
	v_pk_mul_f32 v[112:113], v[112:113], v[118:119] op_sel_hi:[1,0]
	v_pk_mul_f32 v[122:123], v[106:107], v[118:119] op_sel_hi:[1,0]
	v_pk_mul_f32 v[124:125], v[108:109], v[118:119] op_sel_hi:[1,0]
	v_pk_mul_f32 v[102:103], v[102:103], v[118:119] op_sel_hi:[1,0]
	v_pk_mul_f32 v[104:105], v[104:105], v[118:119] op_sel_hi:[1,0]
	s_waitcnt vmcnt(5)
	v_mov_b32_e32 v114, v244
	v_mov_b32_e32 v115, v245
	v_mov_b32_e32 v116, v246
	v_mov_b32_e32 v117, v247
	v_add_u32_e32 v233, 0x80000, v232
	global_load_dwordx4 v[244:247], v233, s[52:53] nt
	v_lshlrev_b32_e32 v106, 16, v114
	v_and_b32_e32 v107, 0xffff0000, v114
	v_lshlrev_b32_e32 v108, 16, v115
	v_and_b32_e32 v109, 0xffff0000, v115
	v_lshlrev_b32_e32 v114, 16, v116
	v_and_b32_e32 v115, 0xffff0000, v116
	v_lshlrev_b32_e32 v116, 16, v117
	v_and_b32_e32 v117, 0xffff0000, v117
	v_pk_fma_f32 v[108:109], v[144:145], v[112:113], v[108:109]
	v_pk_fma_f32 v[106:107], v[142:143], v[110:111], v[106:107]
	v_pk_fma_f32 v[112:113], v[140:141], v[124:125], v[116:117]
	v_pk_fma_f32 v[110:111], v[138:139], v[122:123], v[114:115]
	global_store_dwordx4 v[120:121], v[106:109], off nt
	global_store_dwordx4 v[120:121], v[110:113], off offset:16 nt
	s_nop 1
	v_pk_mul_f32 v[114:115], v[98:99], v[118:119] op_sel_hi:[1,0]
	v_add_u32_e32 v110, 32, v148
	v_ashrrev_i32_e32 v111, 31, v110
	v_pk_mul_f32 v[116:117], v[100:101], v[118:119] op_sel_hi:[1,0]
	v_lshlrev_b64 v[110:111], 11, v[110:111]
	v_lshl_add_u64 v[110:111], v[110:111], 0, v[146:147]
	v_lshl_add_u64 v[112:113], v[110:111], 1, s[52:53]
	s_waitcnt vmcnt(5)
	v_mov_b32_e32 v106, v248
	v_mov_b32_e32 v107, v249
	v_mov_b32_e32 v108, v250
	v_mov_b32_e32 v109, v251
	v_add_u32_e32 v233, 0x80000, v232
	global_load_dwordx4 v[248:251], v233, s[52:53] offset:256 nt
	v_lshlrev_b32_e32 v98, 16, v106
	v_and_b32_e32 v99, 0xffff0000, v106
	v_lshlrev_b32_e32 v100, 16, v107
	v_and_b32_e32 v101, 0xffff0000, v107
	v_lshlrev_b32_e32 v106, 16, v108
	v_and_b32_e32 v107, 0xffff0000, v108
	v_lshlrev_b32_e32 v108, 16, v109
	v_and_b32_e32 v109, 0xffff0000, v109
	v_pk_fma_f32 v[100:101], v[136:137], v[104:105], v[100:101]
	v_pk_fma_f32 v[98:99], v[134:135], v[102:103], v[98:99]
	v_pk_fma_f32 v[104:105], v[132:133], v[116:117], v[108:109]
	v_pk_fma_f32 v[102:103], v[130:131], v[114:115], v[106:107]
	global_store_dwordx4 v[120:121], v[98:101], off offset:512 nt
	global_store_dwordx4 v[120:121], v[102:105], off offset:528 nt
	s_nop 1
	ds_read_b32 v102, v1 offset:8320
	v_lshl_add_u64 v[104:105], v[110:111], 2, s[24:25]
	s_waitcnt lgkmcnt(0)
	v_pk_mul_f32 v[94:95], v[94:95], v[102:103] op_sel_hi:[1,0]
	v_pk_mul_f32 v[96:97], v[96:97], v[102:103] op_sel_hi:[1,0]
	v_pk_mul_f32 v[106:107], v[90:91], v[102:103] op_sel_hi:[1,0]
	v_pk_mul_f32 v[108:109], v[92:93], v[102:103] op_sel_hi:[1,0]
	v_pk_mul_f32 v[86:87], v[86:87], v[102:103] op_sel_hi:[1,0]
	v_pk_mul_f32 v[88:89], v[88:89], v[102:103] op_sel_hi:[1,0]
	s_waitcnt vmcnt(5)
	v_mov_b32_e32 v98, v228
	v_mov_b32_e32 v99, v229
	v_mov_b32_e32 v100, v230
	v_mov_b32_e32 v101, v231
	v_add_u32_e32 v233, 0x90000, v232
	global_load_dwordx4 v[228:231], v233, s[52:53] nt
	v_lshlrev_b32_e32 v90, 16, v98
	v_and_b32_e32 v91, 0xffff0000, v98
	v_lshlrev_b32_e32 v92, 16, v99
	v_and_b32_e32 v93, 0xffff0000, v99
	v_lshlrev_b32_e32 v98, 16, v100
	v_and_b32_e32 v99, 0xffff0000, v100
	v_lshlrev_b32_e32 v100, 16, v101
	v_and_b32_e32 v101, 0xffff0000, v101
	v_pk_fma_f32 v[92:93], v[144:145], v[96:97], v[92:93]
	v_pk_fma_f32 v[90:91], v[142:143], v[94:95], v[90:91]
	v_pk_fma_f32 v[96:97], v[140:141], v[108:109], v[100:101]
	v_pk_fma_f32 v[94:95], v[138:139], v[106:107], v[98:99]
	global_store_dwordx4 v[104:105], v[90:93], off nt
	global_store_dwordx4 v[104:105], v[94:97], off offset:16 nt
	s_nop 1
	v_pk_mul_f32 v[98:99], v[82:83], v[102:103] op_sel_hi:[1,0]
	v_add_u32_e32 v94, 48, v148
	v_ashrrev_i32_e32 v95, 31, v94
	v_pk_mul_f32 v[100:101], v[84:85], v[102:103] op_sel_hi:[1,0]
	v_lshlrev_b64 v[94:95], 11, v[94:95]
	v_lshl_add_u64 v[94:95], v[94:95], 0, v[146:147]
	v_lshl_add_u64 v[96:97], v[94:95], 1, s[52:53]
	s_waitcnt vmcnt(5)
	v_mov_b32_e32 v90, v222
	v_mov_b32_e32 v91, v223
	v_mov_b32_e32 v92, v224
	v_mov_b32_e32 v93, v225
	v_add_u32_e32 v233, 0x90000, v232
	global_load_dwordx4 v[222:225], v233, s[52:53] offset:256 nt
	v_lshlrev_b32_e32 v82, 16, v90
	v_and_b32_e32 v83, 0xffff0000, v90
	v_lshlrev_b32_e32 v84, 16, v91
	v_and_b32_e32 v85, 0xffff0000, v91
	v_lshlrev_b32_e32 v90, 16, v92
	v_and_b32_e32 v91, 0xffff0000, v92
	v_lshlrev_b32_e32 v92, 16, v93
	v_and_b32_e32 v93, 0xffff0000, v93
	v_pk_fma_f32 v[84:85], v[136:137], v[88:89], v[84:85]
	v_pk_fma_f32 v[82:83], v[134:135], v[86:87], v[82:83]
	v_pk_fma_f32 v[88:89], v[132:133], v[100:101], v[92:93]
	v_pk_fma_f32 v[86:87], v[130:131], v[98:99], v[90:91]
	global_store_dwordx4 v[104:105], v[82:85], off offset:512 nt
	global_store_dwordx4 v[104:105], v[86:89], off offset:528 nt
	s_nop 1
	ds_read_b32 v86, v1 offset:8384
	v_lshl_add_u64 v[88:89], v[94:95], 2, s[24:25]
	s_waitcnt lgkmcnt(0)
	v_pk_mul_f32 v[78:79], v[78:79], v[86:87] op_sel_hi:[1,0]
	v_pk_mul_f32 v[80:81], v[80:81], v[86:87] op_sel_hi:[1,0]
	v_pk_mul_f32 v[90:91], v[74:75], v[86:87] op_sel_hi:[1,0]
	v_pk_mul_f32 v[92:93], v[76:77], v[86:87] op_sel_hi:[1,0]
	v_pk_mul_f32 v[70:71], v[70:71], v[86:87] op_sel_hi:[1,0]
	v_pk_mul_f32 v[72:73], v[72:73], v[86:87] op_sel_hi:[1,0]
	s_waitcnt vmcnt(5)
	v_mov_b32_e32 v82, v236
	v_mov_b32_e32 v83, v237
	v_mov_b32_e32 v84, v238
	v_mov_b32_e32 v85, v239
	v_add_u32_e32 v233, 0xa0000, v232
	global_load_dwordx4 v[236:239], v233, s[52:53] nt
	v_lshlrev_b32_e32 v74, 16, v82
	v_and_b32_e32 v75, 0xffff0000, v82
	v_lshlrev_b32_e32 v76, 16, v83
	v_and_b32_e32 v77, 0xffff0000, v83
	v_lshlrev_b32_e32 v82, 16, v84
	v_and_b32_e32 v83, 0xffff0000, v84
	v_lshlrev_b32_e32 v84, 16, v85
	v_and_b32_e32 v85, 0xffff0000, v85
	v_pk_fma_f32 v[76:77], v[144:145], v[80:81], v[76:77]
	v_pk_fma_f32 v[74:75], v[142:143], v[78:79], v[74:75]
	v_pk_fma_f32 v[80:81], v[140:141], v[92:93], v[84:85]
	v_pk_fma_f32 v[78:79], v[138:139], v[90:91], v[82:83]
	global_store_dwordx4 v[88:89], v[74:77], off nt
	global_store_dwordx4 v[88:89], v[78:81], off offset:16 nt
	s_nop 1
	v_pk_mul_f32 v[82:83], v[66:67], v[86:87] op_sel_hi:[1,0]
	v_add_u32_e32 v78, 0x80, v148
	v_ashrrev_i32_e32 v79, 31, v78
	v_pk_mul_f32 v[84:85], v[68:69], v[86:87] op_sel_hi:[1,0]
	v_lshlrev_b64 v[78:79], 11, v[78:79]
	v_lshl_add_u64 v[78:79], v[78:79], 0, v[146:147]
	v_lshl_add_u64 v[80:81], v[78:79], 1, s[52:53]
	s_waitcnt vmcnt(5)
	v_mov_b32_e32 v74, v240
	v_mov_b32_e32 v75, v241
	v_mov_b32_e32 v76, v242
	v_mov_b32_e32 v77, v243
	v_add_u32_e32 v233, 0xa0000, v232
	global_load_dwordx4 v[240:243], v233, s[52:53] offset:256 nt
	v_lshlrev_b32_e32 v66, 16, v74
	v_and_b32_e32 v67, 0xffff0000, v74
	v_lshlrev_b32_e32 v68, 16, v75
	v_and_b32_e32 v69, 0xffff0000, v75
	v_lshlrev_b32_e32 v74, 16, v76
	v_and_b32_e32 v75, 0xffff0000, v76
	v_lshlrev_b32_e32 v76, 16, v77
	v_and_b32_e32 v77, 0xffff0000, v77
	v_pk_fma_f32 v[68:69], v[136:137], v[72:73], v[68:69]
	v_pk_fma_f32 v[66:67], v[134:135], v[70:71], v[66:67]
	v_pk_fma_f32 v[72:73], v[132:133], v[84:85], v[76:77]
	v_pk_fma_f32 v[70:71], v[130:131], v[82:83], v[74:75]
	global_store_dwordx4 v[88:89], v[66:69], off offset:512 nt
	global_store_dwordx4 v[88:89], v[70:73], off offset:528 nt
	s_nop 1
	ds_read_b32 v70, v1 offset:8704
	v_lshl_add_u64 v[72:73], v[78:79], 2, s[24:25]
	s_waitcnt lgkmcnt(0)
	v_pk_mul_f32 v[62:63], v[62:63], v[70:71] op_sel_hi:[1,0]
	v_pk_mul_f32 v[64:65], v[64:65], v[70:71] op_sel_hi:[1,0]
	v_pk_mul_f32 v[74:75], v[58:59], v[70:71] op_sel_hi:[1,0]
	v_pk_mul_f32 v[76:77], v[60:61], v[70:71] op_sel_hi:[1,0]
	v_pk_mul_f32 v[54:55], v[54:55], v[70:71] op_sel_hi:[1,0]
	v_pk_mul_f32 v[56:57], v[56:57], v[70:71] op_sel_hi:[1,0]
	s_waitcnt vmcnt(5)
	v_mov_b32_e32 v66, v244
	v_mov_b32_e32 v67, v245
	v_mov_b32_e32 v68, v246
	v_mov_b32_e32 v69, v247
	v_add_u32_e32 v233, 0xb0000, v232
	global_load_dwordx4 v[244:247], v233, s[52:53] nt
	v_lshlrev_b32_e32 v58, 16, v66
	v_and_b32_e32 v59, 0xffff0000, v66
	v_lshlrev_b32_e32 v60, 16, v67
	v_and_b32_e32 v61, 0xffff0000, v67
	v_lshlrev_b32_e32 v66, 16, v68
	v_and_b32_e32 v67, 0xffff0000, v68
	v_lshlrev_b32_e32 v68, 16, v69
	v_and_b32_e32 v69, 0xffff0000, v69
	v_pk_fma_f32 v[60:61], v[144:145], v[64:65], v[60:61]
	v_pk_fma_f32 v[58:59], v[142:143], v[62:63], v[58:59]
	v_pk_fma_f32 v[64:65], v[140:141], v[76:77], v[68:69]
	v_pk_fma_f32 v[62:63], v[138:139], v[74:75], v[66:67]
	global_store_dwordx4 v[72:73], v[58:61], off nt
	global_store_dwordx4 v[72:73], v[62:65], off offset:16 nt
	s_nop 1
	v_pk_mul_f32 v[66:67], v[50:51], v[70:71] op_sel_hi:[1,0]
	v_add_u32_e32 v62, 0x90, v148
	v_ashrrev_i32_e32 v63, 31, v62
	v_pk_mul_f32 v[68:69], v[52:53], v[70:71] op_sel_hi:[1,0]
	v_lshlrev_b64 v[62:63], 11, v[62:63]
	v_lshl_add_u64 v[62:63], v[62:63], 0, v[146:147]
	v_lshl_add_u64 v[64:65], v[62:63], 1, s[52:53]
	s_waitcnt vmcnt(5)
	v_mov_b32_e32 v58, v248
	v_mov_b32_e32 v59, v249
	v_mov_b32_e32 v60, v250
	v_mov_b32_e32 v61, v251
	v_add_u32_e32 v233, 0xb0000, v232
	global_load_dwordx4 v[248:251], v233, s[52:53] offset:256 nt
	v_lshlrev_b32_e32 v50, 16, v58
	v_and_b32_e32 v51, 0xffff0000, v58
	v_lshlrev_b32_e32 v52, 16, v59
	v_and_b32_e32 v53, 0xffff0000, v59
	v_lshlrev_b32_e32 v58, 16, v60
	v_and_b32_e32 v59, 0xffff0000, v60
	v_lshlrev_b32_e32 v60, 16, v61
	v_and_b32_e32 v61, 0xffff0000, v61
	v_pk_fma_f32 v[52:53], v[136:137], v[56:57], v[52:53]
	v_pk_fma_f32 v[50:51], v[134:135], v[54:55], v[50:51]
	v_pk_fma_f32 v[56:57], v[132:133], v[68:69], v[60:61]
	v_pk_fma_f32 v[54:55], v[130:131], v[66:67], v[58:59]
	global_store_dwordx4 v[72:73], v[50:53], off offset:512 nt
	global_store_dwordx4 v[72:73], v[54:57], off offset:528 nt
	s_nop 1
	ds_read_b32 v54, v1 offset:8768
	v_lshl_add_u64 v[56:57], v[62:63], 2, s[24:25]
	s_waitcnt lgkmcnt(0)
	v_pk_mul_f32 v[46:47], v[46:47], v[54:55] op_sel_hi:[1,0]
	v_pk_mul_f32 v[48:49], v[48:49], v[54:55] op_sel_hi:[1,0]
	v_pk_mul_f32 v[58:59], v[42:43], v[54:55] op_sel_hi:[1,0]
	v_pk_mul_f32 v[60:61], v[44:45], v[54:55] op_sel_hi:[1,0]
	v_pk_mul_f32 v[38:39], v[38:39], v[54:55] op_sel_hi:[1,0]
	v_pk_mul_f32 v[40:41], v[40:41], v[54:55] op_sel_hi:[1,0]
	s_waitcnt vmcnt(5)
	v_mov_b32_e32 v50, v228
	v_mov_b32_e32 v51, v229
	v_mov_b32_e32 v52, v230
	v_mov_b32_e32 v53, v231
	v_lshlrev_b32_e32 v42, 16, v50
	v_and_b32_e32 v43, 0xffff0000, v50
	v_lshlrev_b32_e32 v44, 16, v51
	v_and_b32_e32 v45, 0xffff0000, v51
	v_lshlrev_b32_e32 v50, 16, v52
	v_and_b32_e32 v51, 0xffff0000, v52
	v_lshlrev_b32_e32 v52, 16, v53
	v_and_b32_e32 v53, 0xffff0000, v53
	v_pk_fma_f32 v[44:45], v[144:145], v[48:49], v[44:45]
	v_pk_fma_f32 v[42:43], v[142:143], v[46:47], v[42:43]
	v_pk_fma_f32 v[48:49], v[140:141], v[60:61], v[52:53]
	v_pk_fma_f32 v[46:47], v[138:139], v[58:59], v[50:51]
	global_store_dwordx4 v[56:57], v[42:45], off nt
	global_store_dwordx4 v[56:57], v[46:49], off offset:16 nt
	s_nop 1
	v_pk_mul_f32 v[50:51], v[34:35], v[54:55] op_sel_hi:[1,0]
	v_add_u32_e32 v46, 0xa0, v148
	v_ashrrev_i32_e32 v47, 31, v46
	v_pk_mul_f32 v[52:53], v[36:37], v[54:55] op_sel_hi:[1,0]
	v_lshlrev_b64 v[46:47], 11, v[46:47]
	v_lshl_add_u64 v[46:47], v[46:47], 0, v[146:147]
	v_lshl_add_u64 v[48:49], v[46:47], 1, s[52:53]
	s_waitcnt vmcnt(4)
	v_mov_b32_e32 v42, v222
	v_mov_b32_e32 v43, v223
	v_mov_b32_e32 v44, v224
	v_mov_b32_e32 v45, v225
	v_lshlrev_b32_e32 v34, 16, v42
	v_and_b32_e32 v35, 0xffff0000, v42
	v_lshlrev_b32_e32 v36, 16, v43
	v_and_b32_e32 v37, 0xffff0000, v43
	v_lshlrev_b32_e32 v42, 16, v44
	v_and_b32_e32 v43, 0xffff0000, v44
	v_lshlrev_b32_e32 v44, 16, v45
	v_and_b32_e32 v45, 0xffff0000, v45
	v_pk_fma_f32 v[36:37], v[136:137], v[40:41], v[36:37]
	v_pk_fma_f32 v[34:35], v[134:135], v[38:39], v[34:35]
	v_pk_fma_f32 v[40:41], v[132:133], v[52:53], v[44:45]
	v_pk_fma_f32 v[38:39], v[130:131], v[50:51], v[42:43]
	global_store_dwordx4 v[56:57], v[34:37], off offset:512 nt
	global_store_dwordx4 v[56:57], v[38:41], off offset:528 nt
	s_nop 1
	ds_read_b32 v38, v1 offset:8832
	v_lshl_add_u64 v[40:41], v[46:47], 2, s[24:25]
	s_waitcnt lgkmcnt(0)
	v_pk_mul_f32 v[30:31], v[30:31], v[38:39] op_sel_hi:[1,0]
	v_pk_mul_f32 v[32:33], v[32:33], v[38:39] op_sel_hi:[1,0]
	v_pk_mul_f32 v[42:43], v[26:27], v[38:39] op_sel_hi:[1,0]
	v_pk_mul_f32 v[44:45], v[28:29], v[38:39] op_sel_hi:[1,0]
	v_pk_mul_f32 v[22:23], v[22:23], v[38:39] op_sel_hi:[1,0]
	v_pk_mul_f32 v[24:25], v[24:25], v[38:39] op_sel_hi:[1,0]
	s_waitcnt vmcnt(3)
	v_mov_b32_e32 v34, v236
	v_mov_b32_e32 v35, v237
	v_mov_b32_e32 v36, v238
	v_mov_b32_e32 v37, v239
	v_lshlrev_b32_e32 v26, 16, v34
	v_and_b32_e32 v27, 0xffff0000, v34
	v_lshlrev_b32_e32 v28, 16, v35
	v_and_b32_e32 v29, 0xffff0000, v35
	v_lshlrev_b32_e32 v34, 16, v36
	v_and_b32_e32 v35, 0xffff0000, v36
	v_lshlrev_b32_e32 v36, 16, v37
	v_and_b32_e32 v37, 0xffff0000, v37
	v_pk_fma_f32 v[28:29], v[144:145], v[32:33], v[28:29]
	v_pk_fma_f32 v[26:27], v[142:143], v[30:31], v[26:27]
	v_pk_fma_f32 v[32:33], v[140:141], v[44:45], v[36:37]
	v_pk_fma_f32 v[30:31], v[138:139], v[42:43], v[34:35]
	global_store_dwordx4 v[40:41], v[26:29], off nt
	global_store_dwordx4 v[40:41], v[30:33], off offset:16 nt
	s_nop 1
	v_pk_mul_f32 v[34:35], v[18:19], v[38:39] op_sel_hi:[1,0]
	v_add_u32_e32 v30, 0xb0, v148
	v_ashrrev_i32_e32 v31, 31, v30
	v_pk_mul_f32 v[36:37], v[20:21], v[38:39] op_sel_hi:[1,0]
	v_lshlrev_b64 v[30:31], 11, v[30:31]
	v_lshl_add_u64 v[30:31], v[30:31], 0, v[146:147]
	v_lshl_add_u64 v[32:33], v[30:31], 1, s[52:53]
	s_waitcnt vmcnt(2)
	v_mov_b32_e32 v26, v240
	v_mov_b32_e32 v27, v241
	v_mov_b32_e32 v28, v242
	v_mov_b32_e32 v29, v243
	v_lshlrev_b32_e32 v18, 16, v26
	v_and_b32_e32 v19, 0xffff0000, v26
	v_lshlrev_b32_e32 v20, 16, v27
	v_and_b32_e32 v21, 0xffff0000, v27
	v_lshlrev_b32_e32 v26, 16, v28
	v_and_b32_e32 v27, 0xffff0000, v28
	v_lshlrev_b32_e32 v28, 16, v29
	v_and_b32_e32 v29, 0xffff0000, v29
	v_pk_fma_f32 v[20:21], v[136:137], v[24:25], v[20:21]
	v_pk_fma_f32 v[18:19], v[134:135], v[22:23], v[18:19]
	v_pk_fma_f32 v[24:25], v[132:133], v[36:37], v[28:29]
	v_pk_fma_f32 v[22:23], v[130:131], v[34:35], v[26:27]
	global_store_dwordx4 v[40:41], v[18:21], off offset:512 nt
	global_store_dwordx4 v[40:41], v[22:25], off offset:528 nt
	s_nop 1
	ds_read_b32 v22, v1 offset:8896
	v_lshl_add_u64 v[24:25], v[30:31], 2, s[24:25]
	s_waitcnt lgkmcnt(0)
	v_pk_mul_f32 v[14:15], v[14:15], v[22:23] op_sel_hi:[1,0]
	v_pk_mul_f32 v[16:17], v[16:17], v[22:23] op_sel_hi:[1,0]
	v_pk_mul_f32 v[26:27], v[10:11], v[22:23] op_sel_hi:[1,0]
	v_pk_mul_f32 v[28:29], v[12:13], v[22:23] op_sel_hi:[1,0]
	v_pk_mul_f32 v[6:7], v[6:7], v[22:23] op_sel_hi:[1,0]
	v_pk_mul_f32 v[8:9], v[8:9], v[22:23] op_sel_hi:[1,0]
	s_waitcnt vmcnt(1)
	v_mov_b32_e32 v18, v244
	v_mov_b32_e32 v19, v245
	v_mov_b32_e32 v20, v246
	v_mov_b32_e32 v21, v247
	v_lshlrev_b32_e32 v10, 16, v18
	v_and_b32_e32 v11, 0xffff0000, v18
	v_lshlrev_b32_e32 v12, 16, v19
	v_and_b32_e32 v13, 0xffff0000, v19
	v_lshlrev_b32_e32 v18, 16, v20
	v_and_b32_e32 v19, 0xffff0000, v20
	v_lshlrev_b32_e32 v20, 16, v21
	v_and_b32_e32 v21, 0xffff0000, v21
	v_pk_fma_f32 v[12:13], v[144:145], v[16:17], v[12:13]
	v_pk_fma_f32 v[10:11], v[142:143], v[14:15], v[10:11]
	v_pk_fma_f32 v[16:17], v[140:141], v[28:29], v[20:21]
	v_pk_fma_f32 v[14:15], v[138:139], v[26:27], v[18:19]
	global_store_dwordx4 v[24:25], v[10:13], off nt
	global_store_dwordx4 v[24:25], v[14:17], off offset:16 nt
	s_nop 1
	s_nop 0
	v_pk_mul_f32 v[14:15], v[2:3], v[22:23] op_sel_hi:[1,0]
	v_pk_mul_f32 v[16:17], v[4:5], v[22:23] op_sel_hi:[1,0]
	s_waitcnt vmcnt(0)
	v_mov_b32_e32 v10, v248
	v_mov_b32_e32 v11, v249
	v_mov_b32_e32 v12, v250
	v_mov_b32_e32 v13, v251
	v_lshlrev_b32_e32 v2, 16, v10
	v_and_b32_e32 v3, 0xffff0000, v10
	v_lshlrev_b32_e32 v4, 16, v11
	v_and_b32_e32 v5, 0xffff0000, v11
	v_lshlrev_b32_e32 v10, 16, v12
	v_and_b32_e32 v11, 0xffff0000, v12
	v_lshlrev_b32_e32 v12, 16, v13
	v_and_b32_e32 v13, 0xffff0000, v13
	v_pk_fma_f32 v[4:5], v[136:137], v[8:9], v[4:5]
	v_pk_fma_f32 v[2:3], v[134:135], v[6:7], v[2:3]
	v_pk_fma_f32 v[8:9], v[132:133], v[16:17], v[12:13]
	v_pk_fma_f32 v[6:7], v[130:131], v[14:15], v[10:11]
	global_store_dwordx4 v[24:25], v[2:5], off offset:512 nt
	global_store_dwordx4 v[24:25], v[6:9], off offset:528 nt
	s_nop 1
